# E40: E36 + P0 weight-conversion tile walk rotated by 144 workgroups so the 8-tile workgroups are not the ones that also run the per-token prologue jobs
# speedup vs baseline: 1.0022x; 1.0022x over previous
.LBB0_27:
	s_load_dwordx16 s[40:55], s[78:79], 0x180
	s_load_dwordx16 s[80:95], s[78:79], 0xc0
	s_load_dwordx16 s[56:71], s[78:79], 0x80
	v_lshlrev_b32_e32 v2, 3, v248
	v_and_b32_e32 v2, 56, v2
	s_waitcnt lgkmcnt(0)
	s_add_u32 s14, s54, 0x80000
	s_addc_u32 s15, s55, 0
	s_add_u32 s16, s82, 0x80000
	s_addc_u32 s17, s83, 0
	s_add_u32 s18, s54, 0x40000
	s_addc_u32 s19, s55, 0
	s_add_u32 s20, s56, 0xb00000
	s_addc_u32 s21, s57, 0
	s_load_dwordx16 s[56:71], s[78:79], 0x40
	s_add_u32 s22, s46, 0x580000
	s_addc_u32 s23, s47, 0
	v_mul_u32_u24_e32 v6, 0x101, v2
	v_lshrrev_b32_e32 v35, 3, v248
	s_waitcnt lgkmcnt(0)
	s_add_u32 s24, s66, 0x1600000
	s_addc_u32 s25, s67, 0
	s_add_u32 s26, s44, 0xb00000
	s_addc_u32 s27, s45, 0
	s_load_dwordx16 s[36:51], s[78:79], 0x140
	v_lshlrev_b32_e32 v6, 2, v6
	v_lshlrev_b32_e32 v5, 2, v35
	v_add_u32_e32 v7, 0, v6
	v_add3_u32 v37, 0, v5, v6
	s_waitcnt lgkmcnt(0)
	s_add_u32 s28, s50, 0x1800000
	s_addc_u32 s29, s51, 0
	s_add_u32 s30, s58, 0x1800000
	v_add_u32_e32 v44, v7, v5
	v_or_b32_e32 v5, 0x200, v248
	s_addc_u32 s31, s59, 0
	v_lshrrev_b32_e32 v46, 3, v5
	s_add_u32 s34, s50, 0xc00000
	v_lshlrev_b32_e32 v5, 2, v46
	s_addc_u32 s35, s51, 0
	v_add3_u32 v47, 0, v5, v6
	v_add_u32_e32 v48, v7, v5
	v_or_b32_e32 v5, 0x600, v248
	s_add_u32 s36, s86, 0x80000
	v_and_b32_e32 v36, 0xfc, v32
	v_lshrrev_b32_e32 v49, 3, v5
	s_addc_u32 s37, s87, 0
	v_mov_b32_e32 v39, 0
	v_lshl_add_u32 v3, v36, 2, 0
	v_mul_u32_u24_e32 v4, 0x404, v1
	v_lshlrev_b32_e32 v5, 2, v49
	s_add_u32 s38, s54, 0xc0000
	v_or_b32_e32 v45, 0x80, v35
	v_add3_u32 v50, 0, v5, v6
	v_add_u32_e32 v51, v7, v5
	s_addc_u32 s39, s55, 0
	v_or_b32_e32 v52, 0x80, v46
	v_lshlrev_b32_e32 v40, 2, v36
	v_mov_b32_e32 v41, v39
	v_add_u32_e32 v53, v3, v4
	v_lshlrev_b32_e32 v38, 1, v2
	v_mov_b32_e32 v54, 0x7fffea00
	s_movk_i32 s13, 0xaff
	s_mov_b32 s48, 0x7fffff00
	s_add_i32 s49, s76, 0x90
	s_and_b32 s49, s49, 0xff
	s_branch .LBB0_31
